# P8 epilogue stores regrouped through an adjacent-lane DPP swap so each store covers 8 rows x 128 B (full cache lines) instead of 16 rows x 64 B
# baseline (speedup 1.0000x reference)
.LBB0_939:
	s_add_i32 s20, s40, s38
	s_and_b32 s0, s36, 24
	s_or_b32 s0, s39, s0
	s_lshl_b32 s0, s0, 5
	s_add_i32 s35, s35, 1
	s_add_i32 s24, s24, s25
	s_add_i32 s26, s26, s45
	s_add_i32 s34, s34, s45
	v_and_b32_e32 v130, 15, v238
	v_and_b32_e32 v128, 1, v238
	v_add_u32_e32 v130, s20, v130
	v_lshrrev_b32_e32 v131, 2, v238
	v_and_b32_e32 v131, 12, v131
	v_lshl_add_u32 v130, v130, 10, v131
	v_add_u32_e32 v130, s0, v130
	v_cmp_ne_u32_e32 vcc, 0, v128
	v_lshlrev_b32_e32 v132, 1, v130
	v_add_u32_e32 v133, 0x8000, v132
	v_add_u32_e32 v134, 0x10000, v132
	v_add_u32_e32 v135, 0x18000, v132
	v_add_u32_e32 v136, 0x40000, v132
	v_add_u32_e32 v137, 0x48000, v132
	v_add_u32_e32 v138, 0x50000, v132
	v_add_u32_e32 v139, 0x58000, v132
	global_load_dwordx2 v[150:151], v132, s[46:47]
	global_load_dwordx2 v[152:153], v132, s[46:47] offset:32
	global_load_dwordx2 v[154:155], v133, s[46:47]
	global_load_dwordx2 v[156:157], v133, s[46:47] offset:32
	global_load_dwordx2 v[158:159], v134, s[46:47]
	global_load_dwordx2 v[160:161], v134, s[46:47] offset:32
	global_load_dwordx2 v[162:163], v135, s[46:47]
	global_load_dwordx2 v[164:165], v135, s[46:47] offset:32
	global_load_dwordx2 v[166:167], v132, s[46:47] offset:256
	global_load_dwordx2 v[168:169], v132, s[46:47] offset:288
	global_load_dwordx2 v[170:171], v133, s[46:47] offset:256
	global_load_dwordx2 v[172:173], v133, s[46:47] offset:288
	global_load_dwordx2 v[174:175], v134, s[46:47] offset:256
	global_load_dwordx2 v[176:177], v134, s[46:47] offset:288
	global_load_dwordx2 v[178:179], v135, s[46:47] offset:256
	global_load_dwordx2 v[180:181], v135, s[46:47] offset:288
	global_load_dwordx2 v[182:183], v136, s[46:47]
	global_load_dwordx2 v[184:185], v136, s[46:47] offset:32
	global_load_dwordx2 v[186:187], v137, s[46:47]
	global_load_dwordx2 v[188:189], v137, s[46:47] offset:32
	global_load_dwordx2 v[190:191], v138, s[46:47]
	global_load_dwordx2 v[192:193], v138, s[46:47] offset:32
	global_load_dwordx2 v[194:195], v139, s[46:47]
	global_load_dwordx2 v[196:197], v139, s[46:47] offset:32
	global_load_dwordx2 v[198:199], v136, s[46:47] offset:256
	global_load_dwordx2 v[200:201], v136, s[46:47] offset:288
	global_load_dwordx2 v[202:203], v137, s[46:47] offset:256
	global_load_dwordx2 v[204:205], v137, s[46:47] offset:288
	global_load_dwordx2 v[206:207], v138, s[46:47] offset:256
	global_load_dwordx2 v[208:209], v138, s[46:47] offset:288
	global_load_dwordx2 v[210:211], v139, s[46:47] offset:256
	global_load_dwordx2 v[212:213], v139, s[46:47] offset:288
	v_mov_b32_e32 v149, 0
	v_mov_b32_e32 v214, 0xfffff040
	v_mov_b32_e32 v215, 0x1000
	v_mov_b32_e32 v128, 64
	v_cndmask_b32_e32 v214, v149, v214, vcc
	v_cndmask_b32_e32 v215, v215, v128, vcc
	v_lshlrev_b32_e32 v141, 1, v132
	v_lshlrev_b32_e32 v142, 1, v133
	v_lshlrev_b32_e32 v143, 1, v134
	v_lshlrev_b32_e32 v144, 1, v135
	v_lshlrev_b32_e32 v145, 1, v136
	v_lshlrev_b32_e32 v146, 1, v137
	v_lshlrev_b32_e32 v147, 1, v138
	v_lshlrev_b32_e32 v148, 1, v139
	v_add_u32_e32 v240, v141, v215
	v_add_u32_e32 v141, v141, v214
	v_add_u32_e32 v241, v142, v215
	v_add_u32_e32 v142, v142, v214
	v_add_u32_e32 v242, v143, v215
	v_add_u32_e32 v143, v143, v214
	v_add_u32_e32 v243, v144, v215
	v_add_u32_e32 v144, v144, v214
	v_add_u32_e32 v244, v145, v215
	v_add_u32_e32 v145, v145, v214
	v_add_u32_e32 v245, v146, v215
	v_add_u32_e32 v146, v146, v214
	v_add_u32_e32 v246, v147, v215
	v_add_u32_e32 v147, v147, v214
	v_add_u32_e32 v247, v148, v215
	v_add_u32_e32 v148, v148, v214
	s_waitcnt vmcnt(30)
	v_lshlrev_b32_e32 v214, 16, v150
	v_and_b32_e32 v215, 0xffff0000, v150
	v_lshlrev_b32_e32 v216, 16, v151
	v_and_b32_e32 v217, 0xffff0000, v151
	v_pk_add_f32 v[124:125], v[124:125], v[214:215]
	v_pk_add_f32 v[126:127], v[126:127], v[216:217]
	v_lshlrev_b32_e32 v218, 16, v152
	v_and_b32_e32 v219, 0xffff0000, v152
	v_lshlrev_b32_e32 v220, 16, v153
	v_and_b32_e32 v221, 0xffff0000, v153
	v_pk_add_f32 v[120:121], v[120:121], v[218:219]
	v_pk_add_f32 v[122:123], v[122:123], v[220:221]
	v_cndmask_b32_e32 v222, v120, v124, vcc
	v_cndmask_b32_e32 v223, v121, v125, vcc
	v_cndmask_b32_e32 v224, v122, v126, vcc
	v_cndmask_b32_e32 v225, v123, v127, vcc
	v_mov_b32_dpp v226, v222 quad_perm:[1,0,3,2] row_mask:0xf bank_mask:0xf
	v_mov_b32_dpp v227, v223 quad_perm:[1,0,3,2] row_mask:0xf bank_mask:0xf
	v_mov_b32_dpp v228, v224 quad_perm:[1,0,3,2] row_mask:0xf bank_mask:0xf
	v_mov_b32_dpp v229, v225 quad_perm:[1,0,3,2] row_mask:0xf bank_mask:0xf
	v_cndmask_b32_e32 v230, v124, v226, vcc
	v_cndmask_b32_e32 v231, v125, v227, vcc
	v_cndmask_b32_e32 v232, v126, v228, vcc
	v_cndmask_b32_e32 v233, v127, v229, vcc
	v_cndmask_b32_e32 v234, v226, v120, vcc
	v_cndmask_b32_e32 v235, v227, v121, vcc
	v_cndmask_b32_e32 v236, v228, v122, vcc
	v_cndmask_b32_e32 v237, v229, v123, vcc
	global_store_dwordx4 v141, v[230:233], s[58:59]
	global_store_dwordx4 v240, v[234:237], s[58:59]
	s_waitcnt vmcnt(30)
	v_lshlrev_b32_e32 v214, 16, v154
	v_and_b32_e32 v215, 0xffff0000, v154
	v_lshlrev_b32_e32 v216, 16, v155
	v_and_b32_e32 v217, 0xffff0000, v155
	v_pk_add_f32 v[116:117], v[116:117], v[214:215]
	v_pk_add_f32 v[118:119], v[118:119], v[216:217]
	v_lshlrev_b32_e32 v218, 16, v156
	v_and_b32_e32 v219, 0xffff0000, v156
	v_lshlrev_b32_e32 v220, 16, v157
	v_and_b32_e32 v221, 0xffff0000, v157
	v_pk_add_f32 v[112:113], v[112:113], v[218:219]
	v_pk_add_f32 v[114:115], v[114:115], v[220:221]
	v_cndmask_b32_e32 v222, v112, v116, vcc
	v_cndmask_b32_e32 v223, v113, v117, vcc
	v_cndmask_b32_e32 v224, v114, v118, vcc
	v_cndmask_b32_e32 v225, v115, v119, vcc
	v_mov_b32_dpp v226, v222 quad_perm:[1,0,3,2] row_mask:0xf bank_mask:0xf
	v_mov_b32_dpp v227, v223 quad_perm:[1,0,3,2] row_mask:0xf bank_mask:0xf
	v_mov_b32_dpp v228, v224 quad_perm:[1,0,3,2] row_mask:0xf bank_mask:0xf
	v_mov_b32_dpp v229, v225 quad_perm:[1,0,3,2] row_mask:0xf bank_mask:0xf
	v_cndmask_b32_e32 v230, v116, v226, vcc
	v_cndmask_b32_e32 v231, v117, v227, vcc
	v_cndmask_b32_e32 v232, v118, v228, vcc
	v_cndmask_b32_e32 v233, v119, v229, vcc
	v_cndmask_b32_e32 v234, v226, v112, vcc
	v_cndmask_b32_e32 v235, v227, v113, vcc
	v_cndmask_b32_e32 v236, v228, v114, vcc
	v_cndmask_b32_e32 v237, v229, v115, vcc
	global_store_dwordx4 v142, v[230:233], s[58:59]
	global_store_dwordx4 v241, v[234:237], s[58:59]
	s_waitcnt vmcnt(30)
	v_lshlrev_b32_e32 v214, 16, v158
	v_and_b32_e32 v215, 0xffff0000, v158
	v_lshlrev_b32_e32 v216, 16, v159
	v_and_b32_e32 v217, 0xffff0000, v159
	v_pk_add_f32 v[108:109], v[108:109], v[214:215]
	v_pk_add_f32 v[110:111], v[110:111], v[216:217]
	v_lshlrev_b32_e32 v218, 16, v160
	v_and_b32_e32 v219, 0xffff0000, v160
	v_lshlrev_b32_e32 v220, 16, v161
	v_and_b32_e32 v221, 0xffff0000, v161
	v_pk_add_f32 v[104:105], v[104:105], v[218:219]
	v_pk_add_f32 v[106:107], v[106:107], v[220:221]
	v_cndmask_b32_e32 v222, v104, v108, vcc
	v_cndmask_b32_e32 v223, v105, v109, vcc
	v_cndmask_b32_e32 v224, v106, v110, vcc
	v_cndmask_b32_e32 v225, v107, v111, vcc
	v_mov_b32_dpp v226, v222 quad_perm:[1,0,3,2] row_mask:0xf bank_mask:0xf
	v_mov_b32_dpp v227, v223 quad_perm:[1,0,3,2] row_mask:0xf bank_mask:0xf
	v_mov_b32_dpp v228, v224 quad_perm:[1,0,3,2] row_mask:0xf bank_mask:0xf
	v_mov_b32_dpp v229, v225 quad_perm:[1,0,3,2] row_mask:0xf bank_mask:0xf
	v_cndmask_b32_e32 v230, v108, v226, vcc
	v_cndmask_b32_e32 v231, v109, v227, vcc
	v_cndmask_b32_e32 v232, v110, v228, vcc
	v_cndmask_b32_e32 v233, v111, v229, vcc
	v_cndmask_b32_e32 v234, v226, v104, vcc
	v_cndmask_b32_e32 v235, v227, v105, vcc
	v_cndmask_b32_e32 v236, v228, v106, vcc
	v_cndmask_b32_e32 v237, v229, v107, vcc
	global_store_dwordx4 v143, v[230:233], s[58:59]
	global_store_dwordx4 v242, v[234:237], s[58:59]
	s_waitcnt vmcnt(30)
	v_lshlrev_b32_e32 v214, 16, v162
	v_and_b32_e32 v215, 0xffff0000, v162
	v_lshlrev_b32_e32 v216, 16, v163
	v_and_b32_e32 v217, 0xffff0000, v163
	v_pk_add_f32 v[100:101], v[100:101], v[214:215]
	v_pk_add_f32 v[102:103], v[102:103], v[216:217]
	v_lshlrev_b32_e32 v218, 16, v164
	v_and_b32_e32 v219, 0xffff0000, v164
	v_lshlrev_b32_e32 v220, 16, v165
	v_and_b32_e32 v221, 0xffff0000, v165
	v_pk_add_f32 v[96:97], v[96:97], v[218:219]
	v_pk_add_f32 v[98:99], v[98:99], v[220:221]
	v_cndmask_b32_e32 v222, v96, v100, vcc
	v_cndmask_b32_e32 v223, v97, v101, vcc
	v_cndmask_b32_e32 v224, v98, v102, vcc
	v_cndmask_b32_e32 v225, v99, v103, vcc
	v_mov_b32_dpp v226, v222 quad_perm:[1,0,3,2] row_mask:0xf bank_mask:0xf
	v_mov_b32_dpp v227, v223 quad_perm:[1,0,3,2] row_mask:0xf bank_mask:0xf
	v_mov_b32_dpp v228, v224 quad_perm:[1,0,3,2] row_mask:0xf bank_mask:0xf
	v_mov_b32_dpp v229, v225 quad_perm:[1,0,3,2] row_mask:0xf bank_mask:0xf
	v_cndmask_b32_e32 v230, v100, v226, vcc
	v_cndmask_b32_e32 v231, v101, v227, vcc
	v_cndmask_b32_e32 v232, v102, v228, vcc
	v_cndmask_b32_e32 v233, v103, v229, vcc
	v_cndmask_b32_e32 v234, v226, v96, vcc
	v_cndmask_b32_e32 v235, v227, v97, vcc
	v_cndmask_b32_e32 v236, v228, v98, vcc
	v_cndmask_b32_e32 v237, v229, v99, vcc
	global_store_dwordx4 v144, v[230:233], s[58:59]
	global_store_dwordx4 v243, v[234:237], s[58:59]
	s_waitcnt vmcnt(30)
	v_lshlrev_b32_e32 v214, 16, v166
	v_and_b32_e32 v215, 0xffff0000, v166
	v_lshlrev_b32_e32 v216, 16, v167
	v_and_b32_e32 v217, 0xffff0000, v167
	v_pk_add_f32 v[92:93], v[92:93], v[214:215]
	v_pk_add_f32 v[94:95], v[94:95], v[216:217]
	v_lshlrev_b32_e32 v218, 16, v168
	v_and_b32_e32 v219, 0xffff0000, v168
	v_lshlrev_b32_e32 v220, 16, v169
	v_and_b32_e32 v221, 0xffff0000, v169
	v_pk_add_f32 v[88:89], v[88:89], v[218:219]
	v_pk_add_f32 v[90:91], v[90:91], v[220:221]
	v_cndmask_b32_e32 v222, v88, v92, vcc
	v_cndmask_b32_e32 v223, v89, v93, vcc
	v_cndmask_b32_e32 v224, v90, v94, vcc
	v_cndmask_b32_e32 v225, v91, v95, vcc
	v_mov_b32_dpp v226, v222 quad_perm:[1,0,3,2] row_mask:0xf bank_mask:0xf
	v_mov_b32_dpp v227, v223 quad_perm:[1,0,3,2] row_mask:0xf bank_mask:0xf
	v_mov_b32_dpp v228, v224 quad_perm:[1,0,3,2] row_mask:0xf bank_mask:0xf
	v_mov_b32_dpp v229, v225 quad_perm:[1,0,3,2] row_mask:0xf bank_mask:0xf
	v_cndmask_b32_e32 v230, v92, v226, vcc
	v_cndmask_b32_e32 v231, v93, v227, vcc
	v_cndmask_b32_e32 v232, v94, v228, vcc
	v_cndmask_b32_e32 v233, v95, v229, vcc
	v_cndmask_b32_e32 v234, v226, v88, vcc
	v_cndmask_b32_e32 v235, v227, v89, vcc
	v_cndmask_b32_e32 v236, v228, v90, vcc
	v_cndmask_b32_e32 v237, v229, v91, vcc
	global_store_dwordx4 v141, v[230:233], s[58:59] offset:512
	global_store_dwordx4 v240, v[234:237], s[58:59] offset:512
	s_waitcnt vmcnt(30)
	v_lshlrev_b32_e32 v214, 16, v170
	v_and_b32_e32 v215, 0xffff0000, v170
	v_lshlrev_b32_e32 v216, 16, v171
	v_and_b32_e32 v217, 0xffff0000, v171
	v_pk_add_f32 v[84:85], v[84:85], v[214:215]
	v_pk_add_f32 v[86:87], v[86:87], v[216:217]
	v_lshlrev_b32_e32 v218, 16, v172
	v_and_b32_e32 v219, 0xffff0000, v172
	v_lshlrev_b32_e32 v220, 16, v173
	v_and_b32_e32 v221, 0xffff0000, v173
	v_pk_add_f32 v[80:81], v[80:81], v[218:219]
	v_pk_add_f32 v[82:83], v[82:83], v[220:221]
	v_cndmask_b32_e32 v222, v80, v84, vcc
	v_cndmask_b32_e32 v223, v81, v85, vcc
	v_cndmask_b32_e32 v224, v82, v86, vcc
	v_cndmask_b32_e32 v225, v83, v87, vcc
	v_mov_b32_dpp v226, v222 quad_perm:[1,0,3,2] row_mask:0xf bank_mask:0xf
	v_mov_b32_dpp v227, v223 quad_perm:[1,0,3,2] row_mask:0xf bank_mask:0xf
	v_mov_b32_dpp v228, v224 quad_perm:[1,0,3,2] row_mask:0xf bank_mask:0xf
	v_mov_b32_dpp v229, v225 quad_perm:[1,0,3,2] row_mask:0xf bank_mask:0xf
	v_cndmask_b32_e32 v230, v84, v226, vcc
	v_cndmask_b32_e32 v231, v85, v227, vcc
	v_cndmask_b32_e32 v232, v86, v228, vcc
	v_cndmask_b32_e32 v233, v87, v229, vcc
	v_cndmask_b32_e32 v234, v226, v80, vcc
	v_cndmask_b32_e32 v235, v227, v81, vcc
	v_cndmask_b32_e32 v236, v228, v82, vcc
	v_cndmask_b32_e32 v237, v229, v83, vcc
	global_store_dwordx4 v142, v[230:233], s[58:59] offset:512
	global_store_dwordx4 v241, v[234:237], s[58:59] offset:512
	s_waitcnt vmcnt(30)
	v_lshlrev_b32_e32 v214, 16, v174
	v_and_b32_e32 v215, 0xffff0000, v174
	v_lshlrev_b32_e32 v216, 16, v175
	v_and_b32_e32 v217, 0xffff0000, v175
	v_pk_add_f32 v[76:77], v[76:77], v[214:215]
	v_pk_add_f32 v[78:79], v[78:79], v[216:217]
	v_lshlrev_b32_e32 v218, 16, v176
	v_and_b32_e32 v219, 0xffff0000, v176
	v_lshlrev_b32_e32 v220, 16, v177
	v_and_b32_e32 v221, 0xffff0000, v177
	v_pk_add_f32 v[72:73], v[72:73], v[218:219]
	v_pk_add_f32 v[74:75], v[74:75], v[220:221]
	v_cndmask_b32_e32 v222, v72, v76, vcc
	v_cndmask_b32_e32 v223, v73, v77, vcc
	v_cndmask_b32_e32 v224, v74, v78, vcc
	v_cndmask_b32_e32 v225, v75, v79, vcc
	v_mov_b32_dpp v226, v222 quad_perm:[1,0,3,2] row_mask:0xf bank_mask:0xf
	v_mov_b32_dpp v227, v223 quad_perm:[1,0,3,2] row_mask:0xf bank_mask:0xf
	v_mov_b32_dpp v228, v224 quad_perm:[1,0,3,2] row_mask:0xf bank_mask:0xf
	v_mov_b32_dpp v229, v225 quad_perm:[1,0,3,2] row_mask:0xf bank_mask:0xf
	v_cndmask_b32_e32 v230, v76, v226, vcc
	v_cndmask_b32_e32 v231, v77, v227, vcc
	v_cndmask_b32_e32 v232, v78, v228, vcc
	v_cndmask_b32_e32 v233, v79, v229, vcc
	v_cndmask_b32_e32 v234, v226, v72, vcc
	v_cndmask_b32_e32 v235, v227, v73, vcc
	v_cndmask_b32_e32 v236, v228, v74, vcc
	v_cndmask_b32_e32 v237, v229, v75, vcc
	global_store_dwordx4 v143, v[230:233], s[58:59] offset:512
	global_store_dwordx4 v242, v[234:237], s[58:59] offset:512
	s_waitcnt vmcnt(30)
	v_lshlrev_b32_e32 v214, 16, v178
	v_and_b32_e32 v215, 0xffff0000, v178
	v_lshlrev_b32_e32 v216, 16, v179
	v_and_b32_e32 v217, 0xffff0000, v179
	v_pk_add_f32 v[68:69], v[68:69], v[214:215]
	v_pk_add_f32 v[70:71], v[70:71], v[216:217]
	v_lshlrev_b32_e32 v218, 16, v180
	v_and_b32_e32 v219, 0xffff0000, v180
	v_lshlrev_b32_e32 v220, 16, v181
	v_and_b32_e32 v221, 0xffff0000, v181
	v_pk_add_f32 v[64:65], v[64:65], v[218:219]
	v_pk_add_f32 v[66:67], v[66:67], v[220:221]
	v_cndmask_b32_e32 v222, v64, v68, vcc
	v_cndmask_b32_e32 v223, v65, v69, vcc
	v_cndmask_b32_e32 v224, v66, v70, vcc
	v_cndmask_b32_e32 v225, v67, v71, vcc
	v_mov_b32_dpp v226, v222 quad_perm:[1,0,3,2] row_mask:0xf bank_mask:0xf
	v_mov_b32_dpp v227, v223 quad_perm:[1,0,3,2] row_mask:0xf bank_mask:0xf
	v_mov_b32_dpp v228, v224 quad_perm:[1,0,3,2] row_mask:0xf bank_mask:0xf
	v_mov_b32_dpp v229, v225 quad_perm:[1,0,3,2] row_mask:0xf bank_mask:0xf
	v_cndmask_b32_e32 v230, v68, v226, vcc
	v_cndmask_b32_e32 v231, v69, v227, vcc
	v_cndmask_b32_e32 v232, v70, v228, vcc
	v_cndmask_b32_e32 v233, v71, v229, vcc
	v_cndmask_b32_e32 v234, v226, v64, vcc
	v_cndmask_b32_e32 v235, v227, v65, vcc
	v_cndmask_b32_e32 v236, v228, v66, vcc
	v_cndmask_b32_e32 v237, v229, v67, vcc
	global_store_dwordx4 v144, v[230:233], s[58:59] offset:512
	global_store_dwordx4 v243, v[234:237], s[58:59] offset:512
	s_waitcnt vmcnt(30)
	v_lshlrev_b32_e32 v214, 16, v182
	v_and_b32_e32 v215, 0xffff0000, v182
	v_lshlrev_b32_e32 v216, 16, v183
	v_and_b32_e32 v217, 0xffff0000, v183
	v_pk_add_f32 v[60:61], v[60:61], v[214:215]
	v_pk_add_f32 v[62:63], v[62:63], v[216:217]
	v_lshlrev_b32_e32 v218, 16, v184
	v_and_b32_e32 v219, 0xffff0000, v184
	v_lshlrev_b32_e32 v220, 16, v185
	v_and_b32_e32 v221, 0xffff0000, v185
	v_pk_add_f32 v[56:57], v[56:57], v[218:219]
	v_pk_add_f32 v[58:59], v[58:59], v[220:221]
	v_cndmask_b32_e32 v222, v56, v60, vcc
	v_cndmask_b32_e32 v223, v57, v61, vcc
	v_cndmask_b32_e32 v224, v58, v62, vcc
	v_cndmask_b32_e32 v225, v59, v63, vcc
	v_mov_b32_dpp v226, v222 quad_perm:[1,0,3,2] row_mask:0xf bank_mask:0xf
	v_mov_b32_dpp v227, v223 quad_perm:[1,0,3,2] row_mask:0xf bank_mask:0xf
	v_mov_b32_dpp v228, v224 quad_perm:[1,0,3,2] row_mask:0xf bank_mask:0xf
	v_mov_b32_dpp v229, v225 quad_perm:[1,0,3,2] row_mask:0xf bank_mask:0xf
	v_cndmask_b32_e32 v230, v60, v226, vcc
	v_cndmask_b32_e32 v231, v61, v227, vcc
	v_cndmask_b32_e32 v232, v62, v228, vcc
	v_cndmask_b32_e32 v233, v63, v229, vcc
	v_cndmask_b32_e32 v234, v226, v56, vcc
	v_cndmask_b32_e32 v235, v227, v57, vcc
	v_cndmask_b32_e32 v236, v228, v58, vcc
	v_cndmask_b32_e32 v237, v229, v59, vcc
	global_store_dwordx4 v145, v[230:233], s[58:59]
	global_store_dwordx4 v244, v[234:237], s[58:59]
	s_waitcnt vmcnt(30)
	v_lshlrev_b32_e32 v214, 16, v186
	v_and_b32_e32 v215, 0xffff0000, v186
	v_lshlrev_b32_e32 v216, 16, v187
	v_and_b32_e32 v217, 0xffff0000, v187
	v_pk_add_f32 v[52:53], v[52:53], v[214:215]
	v_pk_add_f32 v[54:55], v[54:55], v[216:217]
	v_lshlrev_b32_e32 v218, 16, v188
	v_and_b32_e32 v219, 0xffff0000, v188
	v_lshlrev_b32_e32 v220, 16, v189
	v_and_b32_e32 v221, 0xffff0000, v189
	v_pk_add_f32 v[48:49], v[48:49], v[218:219]
	v_pk_add_f32 v[50:51], v[50:51], v[220:221]
	v_cndmask_b32_e32 v222, v48, v52, vcc
	v_cndmask_b32_e32 v223, v49, v53, vcc
	v_cndmask_b32_e32 v224, v50, v54, vcc
	v_cndmask_b32_e32 v225, v51, v55, vcc
	v_mov_b32_dpp v226, v222 quad_perm:[1,0,3,2] row_mask:0xf bank_mask:0xf
	v_mov_b32_dpp v227, v223 quad_perm:[1,0,3,2] row_mask:0xf bank_mask:0xf
	v_mov_b32_dpp v228, v224 quad_perm:[1,0,3,2] row_mask:0xf bank_mask:0xf
	v_mov_b32_dpp v229, v225 quad_perm:[1,0,3,2] row_mask:0xf bank_mask:0xf
	v_cndmask_b32_e32 v230, v52, v226, vcc
	v_cndmask_b32_e32 v231, v53, v227, vcc
	v_cndmask_b32_e32 v232, v54, v228, vcc
	v_cndmask_b32_e32 v233, v55, v229, vcc
	v_cndmask_b32_e32 v234, v226, v48, vcc
	v_cndmask_b32_e32 v235, v227, v49, vcc
	v_cndmask_b32_e32 v236, v228, v50, vcc
	v_cndmask_b32_e32 v237, v229, v51, vcc
	global_store_dwordx4 v146, v[230:233], s[58:59]
	global_store_dwordx4 v245, v[234:237], s[58:59]
	s_waitcnt vmcnt(30)
	v_lshlrev_b32_e32 v214, 16, v190
	v_and_b32_e32 v215, 0xffff0000, v190
	v_lshlrev_b32_e32 v216, 16, v191
	v_and_b32_e32 v217, 0xffff0000, v191
	v_pk_add_f32 v[44:45], v[44:45], v[214:215]
	v_pk_add_f32 v[46:47], v[46:47], v[216:217]
	v_lshlrev_b32_e32 v218, 16, v192
	v_and_b32_e32 v219, 0xffff0000, v192
	v_lshlrev_b32_e32 v220, 16, v193
	v_and_b32_e32 v221, 0xffff0000, v193
	v_pk_add_f32 v[40:41], v[40:41], v[218:219]
	v_pk_add_f32 v[42:43], v[42:43], v[220:221]
	v_cndmask_b32_e32 v222, v40, v44, vcc
	v_cndmask_b32_e32 v223, v41, v45, vcc
	v_cndmask_b32_e32 v224, v42, v46, vcc
	v_cndmask_b32_e32 v225, v43, v47, vcc
	v_mov_b32_dpp v226, v222 quad_perm:[1,0,3,2] row_mask:0xf bank_mask:0xf
	v_mov_b32_dpp v227, v223 quad_perm:[1,0,3,2] row_mask:0xf bank_mask:0xf
	v_mov_b32_dpp v228, v224 quad_perm:[1,0,3,2] row_mask:0xf bank_mask:0xf
	v_mov_b32_dpp v229, v225 quad_perm:[1,0,3,2] row_mask:0xf bank_mask:0xf
	v_cndmask_b32_e32 v230, v44, v226, vcc
	v_cndmask_b32_e32 v231, v45, v227, vcc
	v_cndmask_b32_e32 v232, v46, v228, vcc
	v_cndmask_b32_e32 v233, v47, v229, vcc
	v_cndmask_b32_e32 v234, v226, v40, vcc
	v_cndmask_b32_e32 v235, v227, v41, vcc
	v_cndmask_b32_e32 v236, v228, v42, vcc
	v_cndmask_b32_e32 v237, v229, v43, vcc
	global_store_dwordx4 v147, v[230:233], s[58:59]
	global_store_dwordx4 v246, v[234:237], s[58:59]
	s_waitcnt vmcnt(30)
	v_lshlrev_b32_e32 v214, 16, v194
	v_and_b32_e32 v215, 0xffff0000, v194
	v_lshlrev_b32_e32 v216, 16, v195
	v_and_b32_e32 v217, 0xffff0000, v195
	v_pk_add_f32 v[36:37], v[36:37], v[214:215]
	v_pk_add_f32 v[38:39], v[38:39], v[216:217]
	v_lshlrev_b32_e32 v218, 16, v196
	v_and_b32_e32 v219, 0xffff0000, v196
	v_lshlrev_b32_e32 v220, 16, v197
	v_and_b32_e32 v221, 0xffff0000, v197
	v_pk_add_f32 v[32:33], v[32:33], v[218:219]
	v_pk_add_f32 v[34:35], v[34:35], v[220:221]
	v_cndmask_b32_e32 v222, v32, v36, vcc
	v_cndmask_b32_e32 v223, v33, v37, vcc
	v_cndmask_b32_e32 v224, v34, v38, vcc
	v_cndmask_b32_e32 v225, v35, v39, vcc
	v_mov_b32_dpp v226, v222 quad_perm:[1,0,3,2] row_mask:0xf bank_mask:0xf
	v_mov_b32_dpp v227, v223 quad_perm:[1,0,3,2] row_mask:0xf bank_mask:0xf
	v_mov_b32_dpp v228, v224 quad_perm:[1,0,3,2] row_mask:0xf bank_mask:0xf
	v_mov_b32_dpp v229, v225 quad_perm:[1,0,3,2] row_mask:0xf bank_mask:0xf
	v_cndmask_b32_e32 v230, v36, v226, vcc
	v_cndmask_b32_e32 v231, v37, v227, vcc
	v_cndmask_b32_e32 v232, v38, v228, vcc
	v_cndmask_b32_e32 v233, v39, v229, vcc
	v_cndmask_b32_e32 v234, v226, v32, vcc
	v_cndmask_b32_e32 v235, v227, v33, vcc
	v_cndmask_b32_e32 v236, v228, v34, vcc
	v_cndmask_b32_e32 v237, v229, v35, vcc
	global_store_dwordx4 v148, v[230:233], s[58:59]
	global_store_dwordx4 v247, v[234:237], s[58:59]
	s_waitcnt vmcnt(30)
	v_lshlrev_b32_e32 v214, 16, v198
	v_and_b32_e32 v215, 0xffff0000, v198
	v_lshlrev_b32_e32 v216, 16, v199
	v_and_b32_e32 v217, 0xffff0000, v199
	v_pk_add_f32 v[28:29], v[28:29], v[214:215]
	v_pk_add_f32 v[30:31], v[30:31], v[216:217]
	v_lshlrev_b32_e32 v218, 16, v200
	v_and_b32_e32 v219, 0xffff0000, v200
	v_lshlrev_b32_e32 v220, 16, v201
	v_and_b32_e32 v221, 0xffff0000, v201
	v_pk_add_f32 v[24:25], v[24:25], v[218:219]
	v_pk_add_f32 v[26:27], v[26:27], v[220:221]
	v_cndmask_b32_e32 v222, v24, v28, vcc
	v_cndmask_b32_e32 v223, v25, v29, vcc
	v_cndmask_b32_e32 v224, v26, v30, vcc
	v_cndmask_b32_e32 v225, v27, v31, vcc
	v_mov_b32_dpp v226, v222 quad_perm:[1,0,3,2] row_mask:0xf bank_mask:0xf
	v_mov_b32_dpp v227, v223 quad_perm:[1,0,3,2] row_mask:0xf bank_mask:0xf
	v_mov_b32_dpp v228, v224 quad_perm:[1,0,3,2] row_mask:0xf bank_mask:0xf
	v_mov_b32_dpp v229, v225 quad_perm:[1,0,3,2] row_mask:0xf bank_mask:0xf
	v_cndmask_b32_e32 v230, v28, v226, vcc
	v_cndmask_b32_e32 v231, v29, v227, vcc
	v_cndmask_b32_e32 v232, v30, v228, vcc
	v_cndmask_b32_e32 v233, v31, v229, vcc
	v_cndmask_b32_e32 v234, v226, v24, vcc
	v_cndmask_b32_e32 v235, v227, v25, vcc
	v_cndmask_b32_e32 v236, v228, v26, vcc
	v_cndmask_b32_e32 v237, v229, v27, vcc
	global_store_dwordx4 v145, v[230:233], s[58:59] offset:512
	global_store_dwordx4 v244, v[234:237], s[58:59] offset:512
	s_waitcnt vmcnt(30)
	v_lshlrev_b32_e32 v214, 16, v202
	v_and_b32_e32 v215, 0xffff0000, v202
	v_lshlrev_b32_e32 v216, 16, v203
	v_and_b32_e32 v217, 0xffff0000, v203
	v_pk_add_f32 v[20:21], v[20:21], v[214:215]
	v_pk_add_f32 v[22:23], v[22:23], v[216:217]
	v_lshlrev_b32_e32 v218, 16, v204
	v_and_b32_e32 v219, 0xffff0000, v204
	v_lshlrev_b32_e32 v220, 16, v205
	v_and_b32_e32 v221, 0xffff0000, v205
	v_pk_add_f32 v[16:17], v[16:17], v[218:219]
	v_pk_add_f32 v[18:19], v[18:19], v[220:221]
	v_cndmask_b32_e32 v222, v16, v20, vcc
	v_cndmask_b32_e32 v223, v17, v21, vcc
	v_cndmask_b32_e32 v224, v18, v22, vcc
	v_cndmask_b32_e32 v225, v19, v23, vcc
	v_mov_b32_dpp v226, v222 quad_perm:[1,0,3,2] row_mask:0xf bank_mask:0xf
	v_mov_b32_dpp v227, v223 quad_perm:[1,0,3,2] row_mask:0xf bank_mask:0xf
	v_mov_b32_dpp v228, v224 quad_perm:[1,0,3,2] row_mask:0xf bank_mask:0xf
	v_mov_b32_dpp v229, v225 quad_perm:[1,0,3,2] row_mask:0xf bank_mask:0xf
	v_cndmask_b32_e32 v230, v20, v226, vcc
	v_cndmask_b32_e32 v231, v21, v227, vcc
	v_cndmask_b32_e32 v232, v22, v228, vcc
	v_cndmask_b32_e32 v233, v23, v229, vcc
	v_cndmask_b32_e32 v234, v226, v16, vcc
	v_cndmask_b32_e32 v235, v227, v17, vcc
	v_cndmask_b32_e32 v236, v228, v18, vcc
	v_cndmask_b32_e32 v237, v229, v19, vcc
	global_store_dwordx4 v146, v[230:233], s[58:59] offset:512
	global_store_dwordx4 v245, v[234:237], s[58:59] offset:512
	s_waitcnt vmcnt(30)
	v_lshlrev_b32_e32 v214, 16, v206
	v_and_b32_e32 v215, 0xffff0000, v206
	v_lshlrev_b32_e32 v216, 16, v207
	v_and_b32_e32 v217, 0xffff0000, v207
	v_pk_add_f32 v[12:13], v[12:13], v[214:215]
	v_pk_add_f32 v[14:15], v[14:15], v[216:217]
	v_lshlrev_b32_e32 v218, 16, v208
	v_and_b32_e32 v219, 0xffff0000, v208
	v_lshlrev_b32_e32 v220, 16, v209
	v_and_b32_e32 v221, 0xffff0000, v209
	v_pk_add_f32 v[8:9], v[8:9], v[218:219]
	v_pk_add_f32 v[10:11], v[10:11], v[220:221]
	v_cndmask_b32_e32 v222, v8, v12, vcc
	v_cndmask_b32_e32 v223, v9, v13, vcc
	v_cndmask_b32_e32 v224, v10, v14, vcc
	v_cndmask_b32_e32 v225, v11, v15, vcc
	v_mov_b32_dpp v226, v222 quad_perm:[1,0,3,2] row_mask:0xf bank_mask:0xf
	v_mov_b32_dpp v227, v223 quad_perm:[1,0,3,2] row_mask:0xf bank_mask:0xf
	v_mov_b32_dpp v228, v224 quad_perm:[1,0,3,2] row_mask:0xf bank_mask:0xf
	v_mov_b32_dpp v229, v225 quad_perm:[1,0,3,2] row_mask:0xf bank_mask:0xf
	v_cndmask_b32_e32 v230, v12, v226, vcc
	v_cndmask_b32_e32 v231, v13, v227, vcc
	v_cndmask_b32_e32 v232, v14, v228, vcc
	v_cndmask_b32_e32 v233, v15, v229, vcc
	v_cndmask_b32_e32 v234, v226, v8, vcc
	v_cndmask_b32_e32 v235, v227, v9, vcc
	v_cndmask_b32_e32 v236, v228, v10, vcc
	v_cndmask_b32_e32 v237, v229, v11, vcc
	global_store_dwordx4 v147, v[230:233], s[58:59] offset:512
	global_store_dwordx4 v246, v[234:237], s[58:59] offset:512
	s_waitcnt vmcnt(30)
	v_lshlrev_b32_e32 v214, 16, v210
	v_and_b32_e32 v215, 0xffff0000, v210
	v_lshlrev_b32_e32 v216, 16, v211
	v_and_b32_e32 v217, 0xffff0000, v211
	v_pk_add_f32 v[4:5], v[4:5], v[214:215]
	v_pk_add_f32 v[6:7], v[6:7], v[216:217]
	v_lshlrev_b32_e32 v218, 16, v212
	v_and_b32_e32 v219, 0xffff0000, v212
	v_lshlrev_b32_e32 v220, 16, v213
	v_and_b32_e32 v221, 0xffff0000, v213
	v_pk_add_f32 v[0:1], v[0:1], v[218:219]
	v_pk_add_f32 v[2:3], v[2:3], v[220:221]
	v_cndmask_b32_e32 v222, v0, v4, vcc
	v_cndmask_b32_e32 v223, v1, v5, vcc
	v_cndmask_b32_e32 v224, v2, v6, vcc
	v_cndmask_b32_e32 v225, v3, v7, vcc
	v_mov_b32_dpp v226, v222 quad_perm:[1,0,3,2] row_mask:0xf bank_mask:0xf
	v_mov_b32_dpp v227, v223 quad_perm:[1,0,3,2] row_mask:0xf bank_mask:0xf
	v_mov_b32_dpp v228, v224 quad_perm:[1,0,3,2] row_mask:0xf bank_mask:0xf
	v_mov_b32_dpp v229, v225 quad_perm:[1,0,3,2] row_mask:0xf bank_mask:0xf
	v_cndmask_b32_e32 v230, v4, v226, vcc
	v_cndmask_b32_e32 v231, v5, v227, vcc
	v_cndmask_b32_e32 v232, v6, v228, vcc
	v_cndmask_b32_e32 v233, v7, v229, vcc
	v_cndmask_b32_e32 v234, v226, v0, vcc
	v_cndmask_b32_e32 v235, v227, v1, vcc
	v_cndmask_b32_e32 v236, v228, v2, vcc
	v_cndmask_b32_e32 v237, v229, v3, vcc
	global_store_dwordx4 v148, v[230:233], s[58:59] offset:512
	global_store_dwordx4 v247, v[234:237], s[58:59] offset:512
	s_mul_i32 s0, s35, s45
	s_add_i32 s36, s0, s83
	s_cmp_lt_u32 s36, 64
	s_cbranch_scc0 .LBB0_946
